# stack5 + EpiMix bias loads prefetched at unit-loop top (no vmcnt(0) round trip at epilogue start)
# speedup vs baseline: 1.0029x; 1.0019x over previous
;     __device__ __forceinline__ bool next(int i, Unit& u) const {
;         const long L = (long)i * G + c; if (L >= total) return false;
;         if (nM1 == 144 && nN1 == 8 && nM2 == 0 && G == 256) {
;             const int xcd = c & 7, o = c >> 3;
;             const int grp = (i < 4) ? xcd * 4 + i : 32 + (xcd >> 1), idx = (i < 4) ? o : (xcd & 1) * 16 + o;
;             u.pm = grp * 4 + (idx & 3); u.pn = idx >> 2; return true; }
;         int w = (int)L; { const int q = total / NXCD, r = total % NXCD, xcd = w % NXCD, off = w / NXCD; w = (xcd < r ? xcd * (q + 1) : r * (q + 1) + (xcd - r) * q) + off; }
;         int nM = nM1, nN = nN1; const bool second = w >= n1; if (second) { w -= n1; nM = nM2; nN = nN2; }
;         const int wgm = 4;
;         const int nig = wgm * nN, gid = w / nig, fm = gid * wgm, gsz = (nM - fm) < wgm ? (nM - fm) : wgm;
;         int pm = fm + ((w % nig) % gsz), pn = (w % nig) / gsz;
;         if (second) { pm += pm2; pn = pn < split ? a0 + pn : a1 + pn; }
;     __device__ __forceinline__ void operator()(const f32x4 (&acc)[2][2][4][2], const Unit& u, int wr, int wc, int fr_, int fq) const {
;     ...
;         f32x4 bv[2][2];
; #pragma unroll
;         for (int bj = 0; bj < 2; ++bj)
; #pragma unroll
;             for (int n = 0; n < 2; ++n) bv[bj][n] = *(const f32x4*)(bmg + (gate ? colt : 0) + cl + bj * HALF + 4 * n) * (gate ? 1.0f : 0.0f);
.LBB0_591:
	s_lshl_b32 s100, s8, 8
	s_add_i32 s100, s100, 0xfffff200
	s_cmp_gt_i32 s8, 13
	s_cselect_b32 s100, s100, 0
	s_ashr_i32 s101, s100, 31
	v_lshl_add_u64 v[250:251], s[100:101], 2, v[154:155]
	global_load_dwordx4 v[224:227], v[250:251], off
	global_load_dwordx4 v[246:249], v[250:251], off offset:16
	global_load_dwordx4 v[188:191], v[250:251], off offset:528
	s_nop 0
	global_load_dwordx4 v[250:253], v[250:251], off offset:512
	s_add_i32 s93, s93, 1
	s_mul_i32 s6, s93, s56
	s_mul_hi_u32 s7, s93, s42
	s_add_i32 s7, s7, s6
	s_mul_i32 s6, s93, s42
	s_add_u32 s24, s6, s46
	s_addc_u32 s25, s7, s68
	v_mov_b64_e32 v[2:3], s[2:3]
	v_cmp_ge_i64_e32 vcc, s[24:25], v[2:3]
	v_cmp_lt_i64_e64 s[6:7], s[24:25], v[2:3]
	s_cbranch_vccnz .LBB0_593
	s_ashr_i32 s9, s24, 31
	s_lshr_b32 s9, s9, 29
	s_add_i32 s9, s24, s9
	s_ashr_i32 s16, s9, 3
	s_and_b32 s9, s9, -8
	s_sub_i32 s9, s24, s9
	s_lshr_b32 s20, s9, 31
	s_or_b32 s20, s72, s20
	s_mul_i32 s9, s20, s9
	s_add_i32 s9, s9, s16
	s_cmpk_lt_i32 s9, 0x1300
	s_cselect_b32 s21, 0x98, s73
	s_cselect_b32 s16, 0, 0xffffed00
	s_cselect_b32 s20, 0x80, 16
	s_abs_i32 s22, s21
	v_cvt_f32_u32_e32 v2, s22
	s_sub_i32 s25, 0, s22
	s_add_i32 s16, s16, s9
	s_abs_i32 s24, s16
	v_rcp_iflag_f32_e32 v2, v2
	s_xor_b32 s23, s16, s21
	s_ashr_i32 s23, s23, 31
	v_mul_f32_e32 v2, 0x4f7ffffe, v2
	v_cvt_u32_f32_e32 v2, v2
	s_nop 0
	v_readfirstlane_b32 s26, v2
	s_mul_i32 s25, s25, s26
	s_mul_hi_u32 s25, s26, s25
	s_add_i32 s26, s26, s25
	s_mul_hi_u32 s25, s24, s26
	s_mul_i32 s26, s25, s22
	s_sub_i32 s24, s24, s26
	s_add_i32 s27, s25, 1
	s_sub_i32 s26, s24, s22
	s_cmp_ge_u32 s24, s22
	s_cselect_b32 s25, s27, s25
	s_cselect_b32 s24, s26, s24
	s_add_i32 s26, s25, 1
	s_cmp_ge_u32 s24, s22
	s_cselect_b32 s22, s26, s25
	s_xor_b32 s22, s22, s23
	s_sub_i32 s22, s22, s23
	s_lshl_b32 s23, s22, 2
	s_sub_i32 s20, s20, s23
	s_min_i32 s20, s20, 4
	s_abs_i32 s24, s20
	v_cvt_f32_u32_e32 v2, s24
	s_sub_i32 s25, 0, s24
	s_mul_i32 s22, s22, s21
	s_sub_i32 s16, s16, s22
	v_rcp_iflag_f32_e32 v2, v2
	s_abs_i32 s21, s16
	s_xor_b32 s22, s16, s20
	s_ashr_i32 s22, s22, 31
	v_mul_f32_e32 v2, 0x4f7ffffe, v2
	v_cvt_u32_f32_e32 v2, v2
	s_nop 0
	v_readfirstlane_b32 s26, v2
	s_mul_i32 s25, s25, s26
	s_mul_hi_u32 s25, s26, s25
	s_add_i32 s26, s26, s25
	s_mul_hi_u32 s25, s21, s26
	s_mul_i32 s26, s25, s24
	s_sub_i32 s21, s21, s26
	s_add_i32 s27, s25, 1
	s_sub_i32 s26, s21, s24
	s_cmp_ge_u32 s21, s24
	s_cselect_b32 s25, s27, s25
	s_cselect_b32 s21, s26, s21
	s_add_i32 s26, s25, 1
	s_cmp_ge_u32 s21, s24
	s_cselect_b32 s21, s26, s25
	s_xor_b32 s21, s21, s22
	s_sub_i32 s21, s21, s22
	s_mul_i32 s20, s21, s20
	s_sub_i32 s16, s16, s20
	s_add_i32 s16, s16, s23
	s_add_i32 s20, s16, 0x80
	s_cmpk_lt_i32 s9, 0x1300
	s_cselect_b32 s20, s16, s20
	s_cmp_lt_i32 s21, s33
	s_cselect_b32 s16, s47, s65
	s_cmpk_lt_i32 s9, 0x1300
	s_cselect_b32 s9, 0, s16
	s_add_i32 s22, s9, s21

;     __device__ __forceinline__ void operator()(const f32x4 (&acc)[2][2][4][2], const Unit& u, int wr, int wc, int fr_, int fq) const {
;     ...
;         const int pn = u.pn; bf16_t* O; int ld, colt; size_t rowt = (size_t)u.pm * BM; const bool gate = pn >= 14;
;         if (pn < 4) { O = Q; ld = 1024; colt = pn * BM; }
;         else if (pn < 6) { O = (pn == 4) ? K : V; ld = 256; colt = 0; rowt = (u.pm < NLAT_TILES) ? (size_t)(u.pm >> 3) * 2304 + 256 + (size_t)(u.pm & 7) * BM : (size_t)(u.pm - NLAT_TILES) * 2304; }
;         else if (pn < 14) { O = R; ld = 2048; colt = (pn - 6) * BM; }
;         else { O = G; ld = 6144; colt = (pn - 14) * BM; }
.LBB0_597:
	v_mov_b64_e32 v[142:143], v[224:225]
	v_mov_b64_e32 v[144:145], v[226:227]
	v_mov_b64_e32 v[138:139], v[246:247]
	v_mov_b64_e32 v[140:141], v[248:249]
	v_mov_b64_e32 v[130:131], v[188:189]
	v_mov_b64_e32 v[132:133], v[190:191]
	v_mov_b64_e32 v[134:135], v[250:251]
	v_mov_b64_e32 v[136:137], v[252:253]
	v_mov_b32_e32 v188, 0xbfb8aa3b
	v_mov_b32_e32 v189, 0xbfb8aa3b
	v_mov_b32_e32 v190, 1.0
	v_mov_b32_e32 v191, 1.0
	s_ashr_i32 s29, s28, 31
	s_lshl_b64 s[40:41], s[28:29], 8
	v_mov_b32_e32 v162, v168
	s_cmp_gt_i32 s8, 3
	s_mov_b64 s[60:61], -1
	s_cbranch_scc0 .LBB0_611
	s_cmp_gt_u32 s8, 5
	s_mov_b64 s[36:37], -1
	s_cbranch_scc0 .LBB0_604
	s_lshl_b32 s9, s8, 8
	s_cmp_gt_u32 s8, 13
	s_mov_b64 s[0:1], -1
	s_cbranch_scc0 .LBB0_601
	s_add_i32 s34, s9, 0xfffff200
	s_mov_b64 s[0:1], 0

; __device__ __forceinline__ float fast_sigmoid(float x) { return __builtin_amdgcn_rcpf(1.0f + __builtin_amdgcn_exp2f(-1.4426950408889634f * x)); }
;     __device__ __forceinline__ void operator()(const f32x4 (&acc)[2][2][4][2], const Unit& u, int wr, int wc, int fr_, int fq) const {
;     ...
;             for (int n = 0; n < 2; ++n) bv[bj][n] = *(const f32x4*)(bmg + (gate ? colt : 0) + cl + bj * HALF + 4 * n) * (gate ? 1.0f : 0.0f);
;         bf16_t* ob = O + (rowt + wr * 64 + fr) * ld + colt + cl;
; #pragma unroll
;         for (int ai = 0; ai < 2; ++ai)
; #pragma unroll
;             for (int m = 0; m < 4; ++m)
; #pragma unroll
;                 for (int bj = 0; bj < 2; ++bj) { f32x4 v0 = acc[ai][bj][m][0], v1 = acc[ai][bj][m][1];
;                     v0 += bv[bj][0]; v1 += bv[bj][1];
;                     if (gate) {
; #pragma unroll
;                         for (int j = 0; j < 4; ++j) { v0[j] = fast_sigmoid(v0[j]); v1[j] = fast_sigmoid(v1[j]); } }
.LBB0_613:
	s_cmp_gt_i32 s8, 13
	s_cselect_b64 s[28:29], -1, 0
	s_and_b64 s[40:41], s[28:29], exec
	s_cselect_b32 s40, s34, 0
	s_ashr_i32 s41, s40, 31
	v_cndmask_b32_e64 v160, 0, 1.0, s[28:29]
	s_cmp_lt_i32 s8, 14
	v_pk_fma_f32 v[128:129], v[160:161], v[144:145], v[128:129] op_sel_hi:[0,1,1]
	v_pk_fma_f32 v[164:165], v[160:161], v[142:143], v[126:127] op_sel_hi:[0,1,1]
	v_pk_fma_f32 v[126:127], v[160:161], v[140:141], v[124:125] op_sel_hi:[0,1,1]
	v_pk_fma_f32 v[166:167], v[160:161], v[138:139], v[122:123] op_sel_hi:[0,1,1]
	s_cbranch_scc1 .LBB0_615
	v_pk_mul_f32 v[192:193], v[126:127], v[188:189]
	v_pk_mul_f32 v[224:225], v[128:129], v[188:189]
	v_pk_mul_f32 v[226:227], v[164:165], v[188:189]
	v_pk_mul_f32 v[228:229], v[166:167], v[188:189]
	v_exp_f32_e32 v192, v192
	v_exp_f32_e32 v193, v193
	v_exp_f32_e32 v224, v224
	v_exp_f32_e32 v225, v225
	v_exp_f32_e32 v226, v226
	v_exp_f32_e32 v227, v227
	v_exp_f32_e32 v228, v228
	v_exp_f32_e32 v229, v229
	v_pk_add_f32 v[192:193], v[192:193], v[190:191]
	v_pk_add_f32 v[224:225], v[224:225], v[190:191]
	v_pk_add_f32 v[226:227], v[226:227], v[190:191]
	v_pk_add_f32 v[228:229], v[228:229], v[190:191]
	v_rcp_f32_e32 v126, v192
	v_rcp_f32_e32 v127, v193
	v_rcp_f32_e32 v128, v224
	v_rcp_f32_e32 v129, v225
	v_rcp_f32_e32 v164, v226
	v_rcp_f32_e32 v165, v227
	v_rcp_f32_e32 v166, v228
	v_rcp_f32_e32 v167, v229
